# persistent mixer queues: the wait for the prefetched next unit index moved from right after the atomic to a point inside the unit where vmcnt(0) already holds (dedicated return VGPR)
# baseline (speedup 1.0000x reference)
; __device__ __forceinline__ void phase_mixer(const Params& p, LAS unsigned char* lds) {
;     ...
;         unsigned* q = (unsigned*)p.ws + 4096 + 64 * x;
;         int nxt = 0;
;         if (tid == 0) nxt = (int)__hip_atomic_fetch_add(q, 1u, __ATOMIC_RELAXED, __HIP_MEMORY_SCOPE_AGENT);
.LBB0_964:
	s_or_b64 exec, exec, s[4:5]
	s_waitcnt vmcnt(0)
	v_readfirstlane_b32 s4, v1
	s_nop 1
	v_add_u32_e32 v191, s4, v0
	v_mov_b32_e32 v241, v191

; #define LAS __attribute__((address_space(3)))
; __device__ __forceinline__ int rfl(int v) { return __builtin_amdgcn_readfirstlane(v); }
; __device__ __forceinline__ void dsa_unit(const Params& p, LAS unsigned char* lds, int b, int c) {
;     ...
;     if (c <= 3) { for (int i = tid; i < 64 * 256; i += 512) selall[i] = (unsigned short)(((i & 255) < N) ? (i & 255) : 0); }
;     else {
;         const int r32 = lane & 31, ql = 32 * (wid & 1) + r32;
;         {
;           const int qq = tid >> 3, ch = tid & 7;
; #pragma unroll
;           for (int i = 0; i < 4; ++i) { const int pc = ch + 8 * i; const u32x4 v = *(const u32x4*)(Zb + (size_t)(t0 + qq) * NZ + ZIQ + pc * 8); *(LAS u32x4*)(lds + DS_IQ + qq * 528 + pc * 16) = v; }
;           ((LAS float*)(lds + DS_WQ))[ch * 64 + qq] = ((const float*)(p.ws + WS_WQ))[(rowb + t0 + qq) * 8 + ch]; }
;         if (tid < 64) { prefv[tid] = 0u; remv[tid] = 256u; cntv[tid] = 0u; ccntv[tid] = 0u; }
; __device__ __forceinline__ void phase_mixer(const Params& p, LAS unsigned char* lds) {
;     ...
;         for (;;) {
;             if (tid == 0) slot[0] = nxt;
;             __syncthreads();
;             const int u = rfl(slot[0]);
;             if (u >= 128) break;
;             if (tid == 0) nxt = (int)__hip_atomic_fetch_add(q, 1u, __ATOMIC_RELAXED, __HIP_MEMORY_SCOPE_AGENT);
;             dsa_unit(p, lds, x, 127 - u);
.LBB0_968:
	s_mov_b64 s[0:1], exec
	v_readlane_b32 s2, v240, 3
	v_readlane_b32 s3, v240, 4
	s_and_b64 s[2:3], s[0:1], s[2:3]
	s_mov_b64 exec, s[2:3]
	v_mov_b32_e32 v0, s59
	ds_write_b32 v0, v191
	s_or_b64 exec, exec, s[0:1]
	v_mov_b32_e32 v0, s59
	s_waitcnt lgkmcnt(0)
	s_barrier
	ds_read_b32 v0, v0
	s_mov_b64 s[0:1], -1
	s_waitcnt lgkmcnt(0)
	v_readfirstlane_b32 s20, v0
	s_cmpk_gt_i32 s20, 0x7f
	s_cbranch_scc1 .LBB0_967
	s_mov_b64 s[0:1], exec
	v_readlane_b32 s2, v240, 3
	v_readlane_b32 s3, v240, 4
	s_and_b64 s[2:3], s[0:1], s[2:3]
	s_mov_b64 exec, s[2:3]
	s_cbranch_execz .LBB0_975
	s_mov_b64 s[18:19], exec
	v_mbcnt_lo_u32_b32 v0, s18, 0
	v_mbcnt_hi_u32_b32 v0, s19, v0
	v_cmp_eq_u32_e32 vcc, 0, v0
	s_and_saveexec_b64 s[2:3], vcc
	s_cbranch_execz .LBB0_974
	s_bcnt1_i32_b64 s18, s[18:19]
	v_mov_b32_e32 v1, s18
	v_readlane_b32 s18, v240, 7
	v_readlane_b32 s19, v240, 8
	s_nop 4
	global_atomic_add v241, v155, v1, s[18:19] sc0
.LBB0_974:
	s_or_b64 exec, exec, s[2:3]
.LBB0_975:
	s_or_b64 exec, exec, s[0:1]
	s_sub_i32 s2, 0x7f, s20
	v_readfirstlane_b32 s3, v144
	s_lshr_b32 s69, s3, 6
	s_lshl_b32 s70, s2, 6
	s_cmp_gt_u32 s2, 3
	s_mov_b64 s[0:1], -1
	s_cbranch_scc0 .LBB0_1816
	v_add_u32_e32 v2, s70, v146
	v_mov_b64_e32 v[0:1], s[36:37]
	v_mad_u64_u32 v[0:1], s[0:1], v2, s61, v[0:1]
	s_mov_b64 s[0:1], 0x1100
	s_nop 0
	v_lshl_add_u64 v[8:9], v[0:1], 0, s[0:1]
	v_lshlrev_b32_e32 v154, 1, v148
	v_mov_b32_e32 v165, v155
	v_mov_b32_e32 v167, v155
	v_mov_b32_e32 v169, v155
	v_lshl_add_u64 v[0:1], v[8:9], 0, v[154:155]
	v_lshl_add_u64 v[4:5], v[8:9], 0, v[164:165]
	v_lshl_add_u64 v[10:11], v[8:9], 0, v[166:167]
	v_lshl_add_u64 v[12:13], v[8:9], 0, v[168:169]
	global_load_dwordx4 v[0:3], v[0:1], off
	s_nop 0
	global_load_dwordx4 v[4:7], v[4:5], off
	s_nop 0
	global_load_dwordx4 v[8:11], v[10:11], off
	s_nop 0
	global_load_dwordx4 v[12:15], v[12:13], off
	s_add_i32 s34, s70, s46
	v_lshl_add_u64 v[16:17], s[34:35], 0, v[146:147]
	v_lshlrev_b64 v[16:17], 5, v[16:17]
	v_lshl_add_u64 v[16:17], v[156:157], 0, v[16:17]
	global_load_dword v16, v[16:17], off
	v_add_u32_e32 v17, v193, v187
	s_waitcnt vmcnt(4)
	ds_write_b128 v17, v[0:3]
	s_waitcnt vmcnt(3)
	ds_write_b128 v219, v[4:7]
	s_waitcnt vmcnt(2)
	ds_write_b128 v220, v[8:11]
	s_waitcnt vmcnt(1)
	ds_write_b128 v221, v[12:15]
	s_waitcnt vmcnt(0)
	ds_write_b32 v194, v16
	s_and_saveexec_b64 s[0:1], s[6:7]
	s_cbranch_execz .LBB0_978
	ds_write_b32 v195, v155
	ds_write_b32 v196, v200
	ds_write_b32 v197, v155
	ds_write_b32 v198, v155

;     ...
;         a0 = n0; a1 = n1;
;     }
.Lm6_nb15:
	s_mov_b64 exec, -1
	s_waitcnt vmcnt(0)
	v_mov_b64_e32 v[132:133], v[64:65]
	v_mov_b64_e32 v[134:135], v[66:67]
	v_mov_b64_e32 v[128:129], v[68:69]
	v_mov_b64_e32 v[130:131], v[70:71]
	s_cmp_lg_u32 s25, s1
	s_mov_b32 s18, s1
	s_cbranch_scc1 .Lm6_loop
	s_nop 0
	s_nop 0
.LBB0_1620:
	s_mov_b64 s[0:1], 0

; #define LAS __attribute__((address_space(3)))
; #define G_KLOAD(dst, SELP, kb0, cnt) do { _Pragma("unroll") for (int i_ = 0; i_ < (cnt); ++i_) { const int s_ = (SELP)[16 * ((kb0) + i_) + n]; const bf16_t* kp_ = Zb + (size_t)s_ * NZ + ZDK + g * 8; \
;         dst[2 * i_] = *(const bf16x8*)kp_; dst[2 * i_ + 1] = *(const bf16x8*)(kp_ + 32); } asm volatile("" ::: "memory"); } while (0)
; __device__ __forceinline__ void dsa_unit(const Params& p, LAS unsigned char* lds, int b, int c) {
;     ...
;     __syncthreads();
;     const int n = lane & 15, g = lane >> 4, trq = (lane & 15) >> 2, trp = lane & 3;
;     LAS unsigned char* vst = lds + DS_VST + wid * 8192;
;     ...
;     bf16x8 kA[8], qfn0, qfn1;
;     { LAS const unsigned short* sel0 = selall + wid * 256; G_KLOAD(kA, sel0, 0, 4);
;       const bf16_t* qp = Z + (rowb + t0 + wid) * NZ + ZDQ + (n & 7) * 64 + g * 8; qfn0 = *(const bf16x8*)qp; qfn1 = *(const bf16x8*)(qp + 32); }
.LBB0_1820:
	s_waitcnt vmcnt(0)
	s_mov_b64 s[98:99], exec
	v_readlane_b32 s100, v240, 3
	v_readlane_b32 s101, v240, 4
	s_and_b64 s[100:101], s[98:99], s[100:101]
	s_mov_b64 exec, s[100:101]
	v_mov_b32_e32 v191, v241
	s_mov_b64 exec, s[98:99]
	s_lshl_b32 s3, s69, 9
	v_add_u32_e32 v0, s3, v209
	s_waitcnt lgkmcnt(0)
	s_barrier
	ds_read_u16 v1, v0
	ds_read_u16 v2, v0 offset:32
	ds_read_u16 v6, v0 offset:64
	ds_read_u16 v7, v0 offset:96
	v_lshlrev_b32_e32 v172, 1, v158
	v_mov_b32_e32 v173, v155
	s_waitcnt lgkmcnt(3)
	v_mul_u32_u24_e32 v154, 0x2400, v1
	s_waitcnt lgkmcnt(2)
	v_mul_u32_u24_e32 v0, 0x2400, v2
	v_lshl_add_u64 v[2:3], s[36:37], 0, v[154:155]
	v_lshl_add_u64 v[2:3], v[2:3], 0, v[172:173]
	v_mov_b32_e32 v1, v155
	v_lshl_add_u64 v[4:5], v[2:3], 0, s[38:39]
	v_add_co_u32_e32 v2, vcc, s66, v2
	v_lshl_add_u64 v[0:1], s[36:37], 0, v[0:1]
	s_nop 0
	v_addc_co_u32_e32 v3, vcc, 0, v3, vcc
	v_lshl_add_u64 v[0:1], v[0:1], 0, v[172:173]
	global_load_dwordx4 v[16:19], v[2:3], off
	global_load_dwordx4 v[20:23], v[4:5], off offset:64
	v_lshl_add_u64 v[2:3], v[0:1], 0, s[38:39]
	v_add_co_u32_e32 v0, vcc, s66, v0
	s_waitcnt lgkmcnt(1)
	v_mul_u32_u24_e32 v154, 0x2400, v6
	v_addc_co_u32_e32 v1, vcc, 0, v1, vcc
	global_load_dwordx4 v[8:11], v[0:1], off
	global_load_dwordx4 v[12:15], v[2:3], off offset:64
	v_lshl_add_u64 v[2:3], s[36:37], 0, v[154:155]
	s_waitcnt lgkmcnt(0)
	v_mul_u32_u24_e32 v0, 0x2400, v7
	v_lshl_add_u64 v[2:3], v[2:3], 0, v[172:173]
	v_mov_b32_e32 v1, v155
	s_lshl_b32 s0, s69, 13
	v_lshl_add_u64 v[4:5], v[2:3], 0, s[38:39]
	v_add_co_u32_e32 v2, vcc, s66, v2
	v_lshl_add_u64 v[0:1], s[36:37], 0, v[0:1]
	s_min_i32 s2, s2, 0x100
	v_addc_co_u32_e32 v3, vcc, 0, v3, vcc
	v_lshl_add_u64 v[0:1], v[0:1], 0, v[172:173]
	s_add_i32 s18, s0, 0x100
	global_load_dwordx4 v[32:35], v[2:3], off
	global_load_dwordx4 v[36:39], v[4:5], off offset:64
	v_lshl_add_u64 v[2:3], v[0:1], 0, s[38:39]
	v_add_co_u32_e32 v0, vcc, s66, v0
	s_add_u32 s0, s34, s69
	s_nop 0
	v_addc_co_u32_e32 v1, vcc, 0, v1, vcc
	s_addc_u32 s1, s35, 0
	global_load_dwordx4 v[40:43], v[0:1], off
	global_load_dwordx4 v[44:47], v[2:3], off offset:64
	s_mul_i32 s19, s1, 0x2400
	v_mad_u64_u32 v[0:1], s[0:1], s0, v223, v[160:161]
	v_add_u32_e32 v1, s19, v1
	global_load_dwordx4 v[4:7], v[0:1], off offset:3072
	s_nop 0
	global_load_dwordx4 v[0:3], v[0:1], off offset:3136
	s_add_u32 s0, s34, s69
	s_addc_u32 s1, s35, 0
	v_add_u32_e32 v24, s18, v211
	v_add_u32_e32 v25, s18, v188
	s_lshl_b64 s[0:1], s[0:1], 10
	s_mov_b32 s20, 0
	v_sub_u32_e32 v165, s2, v210
	v_add_u32_e32 v167, s3, v217
	v_lshl_add_u64 v[174:175], v[162:163], 0, s[0:1]
	v_add_u32_e32 v169, s3, v218
	v_add_u32_e32 v176, v24, v212
	v_add_u32_e32 v177, v25, v213
	s_branch .LBB0_1822

; __device__ __forceinline__ void phase_mixer(const Params& p, LAS unsigned char* lds) {
;     ...
;         unsigned* q = (unsigned*)p.ws + 4096 + 64 * x + 32;
;         int nxt = 0;
;         if (tid == 0) nxt = (int)__hip_atomic_fetch_add(q, 1u, __ATOMIC_RELAXED, __HIP_MEMORY_SCOPE_AGENT);
.LBB0_1827:
	s_or_b64 exec, exec, s[2:3]
	s_waitcnt vmcnt(0)
	v_readfirstlane_b32 s2, v5
	s_nop 1
	v_add_u32_e32 v108, s2, v4
	v_mov_b32_e32 v242, v108

; __device__ __forceinline__ int rfl(int v) { return __builtin_amdgcn_readfirstlane(v); }
; __device__ __forceinline__ void fox_unit(const Params& p, LAS unsigned char* lds, int b, int h, int qb, float thr2) {
;     ...
;     const int NT = 4 * qb + 4;
;     const int kt_my_last = qw >> 6, st_last = NT / 2 - 1;
;     const int srow = tid >> 3, sch = tid & 7;
;     const bf16_t* kg = Z + (rowb + srow) * NZ + ZK + h * 64 + sch * 8; const bf16_t* vg = Z + (rowb + srow) * NZ + ZV + h * 64 + sch * 8;
;     u32x4 kra, krb, vra, vrb; float freg = 0.f;
; __device__ __forceinline__ void phase_mixer(const Params& p, LAS unsigned char* lds) {
;     ...
;         for (;;) {
;             if (tid == 0) slot[1] = nxt;
;             __syncthreads();
;             const int v = rfl(slot[1]);
;             if (v >= 256) break;
;             if (tid == 0) nxt = (int)__hip_atomic_fetch_add(q, 1u, __ATOMIC_RELAXED, __HIP_MEMORY_SCOPE_AGENT);
;             fox_unit(p, lds, v & 7, x, 31 - (v >> 3), thr2);
.LBB0_1831:
	s_mov_b64 s[0:1], exec
	v_readlane_b32 s2, v240, 3
	v_readlane_b32 s3, v240, 4
	s_and_b64 s[2:3], s[0:1], s[2:3]
	s_mov_b64 exec, s[2:3]
	v_mov_b32_e32 v0, s79
	ds_write_b32 v0, v108
	s_or_b64 exec, exec, s[0:1]
	v_mov_b32_e32 v0, s79
	s_waitcnt lgkmcnt(0)
	s_barrier
	ds_read_b32 v0, v0
	s_waitcnt lgkmcnt(0)
	v_readfirstlane_b32 s8, v0
	s_cmpk_gt_i32 s8, 0xff
	s_cselect_b64 s[90:91], -1, 0
	s_and_b64 vcc, exec, s[90:91]
	s_cbranch_vccnz .LBB0_1830
	s_mov_b64 s[0:1], exec
	v_readlane_b32 s2, v240, 3
	v_readlane_b32 s3, v240, 4
	s_and_b64 s[2:3], s[0:1], s[2:3]
	s_mov_b64 exec, s[2:3]
	s_cbranch_execz .LBB0_1838
	s_mov_b64 s[10:11], exec
	v_mbcnt_lo_u32_b32 v0, s10, 0
	v_mbcnt_hi_u32_b32 v0, s11, v0
	v_cmp_eq_u32_e32 vcc, 0, v0
	s_and_saveexec_b64 s[2:3], vcc
	s_cbranch_execz .LBB0_1837
	s_bcnt1_i32_b64 s9, s[10:11]
	v_readlane_b32 s10, v240, 19
	v_mov_b32_e32 v2, s9
	v_readlane_b32 s11, v240, 20
	s_nop 4
	global_atomic_add v242, v1, v2, s[10:11] sc0
.LBB0_1837:
	s_or_b64 exec, exec, s[2:3]
.LBB0_1838:
	s_or_b64 exec, exec, s[0:1]
	s_and_b32 s2, s8, 7
	s_ashr_i32 s8, s8, 3
	s_lshl_b32 s0, s2, 18
	s_sub_i32 s11, 31, s8
	s_or_b32 s0, s0, s20
	s_add_u32 s0, s18, s0
	s_addc_u32 s1, s19, 0
	s_lshl_b32 s12, s2, 13
	s_lshl_b32 s10, s11, 2
	v_or_b32_e32 v0, s12, v146
	s_add_i32 s2, s10, 4
	v_mul_u32_u24_e32 v0, 0x1200, v0
	s_lshr_b32 s9, s2, 1
	v_lshlrev_b32_e32 v0, 1, v0
	s_add_i32 s13, s9, -1
	v_lshl_add_u64 v[104:105], v[102:103], 0, v[0:1]
	v_mad_u64_u32 v[2:3], s[2:3], s13, v157, v[104:105]
	v_add_co_u32_e32 v4, vcc, 0x90000, v2
	v_readfirstlane_b32 s14, v144
	s_nop 0
	v_addc_co_u32_e32 v5, vcc, 0, v3, vcc
	global_load_dwordx4 v[66:69], v[2:3], off offset:1024
	global_load_dwordx4 v[70:73], v[2:3], off offset:2048
	global_load_dwordx4 v[74:77], v[4:5], off offset:1024
	global_load_dwordx4 v[78:81], v[4:5], off offset:2048
	v_mov_b32_e32 v2, 0
	s_waitcnt vmcnt(36)
	v_mov_b32_e32 v107, 0
	s_and_saveexec_b64 s[2:3], s[6:7]
	s_cbranch_execz .LBB0_1840
	v_lshl_or_b32 v0, s13, 7, v144
	v_lshl_add_u64 v[4:5], v[0:1], 2, s[0:1]
	global_load_dword v107, v[4:5], off

; #define FX_STORE(bf) do { *(LAS u32x4*)(Kl + (2 * (bf)) * KBYTES + srow * KST + sch * 16) = kra; *(LAS u32x4*)(Kl + (2 * (bf) + 1) * KBYTES + srow * KST + sch * 16) = krb; \
;         *(LAS u32x4*)(Vl + (2 * (bf)) * KBYTES + srow * KST + sch * 16) = vra; *(LAS u32x4*)(Vl + (2 * (bf) + 1) * KBYTES + srow * KST + sch * 16) = vrb; if (tid < 128) Fl[(bf) * 128 + tid] = Fref - freg; } while (0)
; __device__ __forceinline__ void fox_unit(const Params& p, LAS unsigned char* lds, int b, int h, int qb, float thr2) {
;     ...
;     { const float Fw = F2[qw]; const int ta = lane, tb = lane + 64;
;       const float fu = tid < NT - 4 ? F2[64 * tid + 63] : 0.f, fa = ta < NT - 4 ? F2[64 * ta + 63] : 0.f, fb = tb < NT - 4 ? F2[64 * tb + 63] : 0.f;
;       kt0 = __syncthreads_count((tid < NT - 4 && (fu - Fref) > thr2) ? 1 : 0);
;       const bool pa = ta < NT - 4 && (fa - Fw) > thr2, pb = tb < NT - 4 && (fb - Fw) > thr2;
;       ktw = __popcll(__ballot(pa)) + __popcll(__ballot(pb)); }
;     ...
;     float m_run = -INFINITY, l_run = 0.f; f32x16 o0, o1;
; #pragma unroll
;     for (int r = 0; r < 16; ++r) { o0[r] = 0.f; o1[r] = 0.f; }
;     const int st0 = kt0 >> 1;
;     FX_STORE(0); __syncthreads();
;     const int trq = (lane & 15) >> 2, trp = lane & 3;
.LBB0_1853:
	v_sub_f32_e32 v2, v5, v0
	v_cmp_gt_f32_e64 s[2:3], v2, v110
	v_sub_f32_e32 v0, v4, v0
	v_cmp_gt_f32_e64 s[12:13], v0, v110
	s_and_b64 s[2:3], vcc, s[2:3]
	v_cndmask_b32_e64 v0, 0, 1, s[2:3]
	s_and_b64 s[2:3], s[10:11], s[12:13]
	v_cmp_ne_u32_e32 vcc, 0, v0
	v_cndmask_b32_e64 v0, 0, 1, s[2:3]
	v_cmp_ne_u32_e64 s[10:11], 0, v0
	ds_write_b128 v111, v[66:69]
	ds_write_b128 v111, v[74:77] offset:9216
	ds_write_b128 v111, v[70:73] offset:36864
	ds_write_b128 v111, v[78:81] offset:46080
	s_and_saveexec_b64 s[2:3], s[6:7]
	v_sub_f32_e32 v0, v160, v107
	ds_write_b32 v112, v0
	s_or_b64 exec, exec, s[2:3]
	s_waitcnt vmcnt(0)
	s_mov_b64 s[98:99], exec
	v_readlane_b32 s100, v240, 3
	v_readlane_b32 s101, v240, 4
	s_and_b64 s[100:101], s[98:99], s[100:101]
	s_mov_b64 exec, s[100:101]
	v_mov_b32_e32 v108, v242
	s_mov_b64 exec, s[98:99]
	s_lshl_b32 s2, s16, 8
	s_add_i32 s33, s2, 0x100
	s_ashr_i32 s96, s17, 1
	s_add_i32 s33, s33, 0x12400
	s_cmp_le_i32 s9, s96
	v_lshl_add_u32 v161, v151, 2, s33
	s_waitcnt lgkmcnt(0)
	s_barrier
	s_cbranch_scc1 .LBB0_1886
	s_bcnt1_i32_b64 s2, vcc
	s_bcnt1_i32_b64 s97, s[10:11]
	v_and_or_b32 v0, s86, 32, v151
	s_add_i32 s97, s97, s2
	v_cmp_gt_u32_e64 s[10:11], v159, v0
	v_cmp_gt_u32_e64 s[12:13], v113, v0
	v_cmp_lt_u32_e64 s[14:15], v159, v0
	v_cmp_gt_u32_e64 s[16:17], v114, v0
	v_cmp_gt_u32_e64 s[18:19], v115, v0
	v_cmp_gt_u32_e64 s[20:21], v116, v0
	v_cmp_gt_u32_e64 s[22:23], v117, v0
	v_cmp_gt_u32_e64 s[24:25], v118, v0
	v_cmp_gt_u32_e64 s[26:27], v119, v0
	v_cmp_gt_u32_e64 s[28:29], v120, v0
	v_cmp_gt_u32_e64 s[30:31], v121, v0
	v_cmp_gt_u32_e64 s[34:35], v122, v0
	v_cmp_gt_u32_e64 s[36:37], v123, v0
	v_cmp_gt_u32_e64 s[38:39], v124, v0
	v_cmp_gt_u32_e64 s[40:41], v125, v0
	v_cmp_gt_u32_e64 s[42:43], v126, v0
	v_cmp_gt_u32_e64 s[44:45], v127, v0
	v_cmp_gt_u32_e64 s[46:47], v128, v0
	v_cmp_gt_u32_e64 s[48:49], v129, v0
	v_cmp_gt_u32_e64 s[50:51], v130, v0
	v_cmp_gt_u32_e64 s[52:53], v131, v0
	v_cmp_gt_u32_e64 s[54:55], v132, v0
	v_cmp_gt_u32_e64 s[56:57], v133, v0
	v_cmp_gt_u32_e64 s[58:59], v134, v0
	v_cmp_gt_u32_e64 s[60:61], v135, v0
	v_cmp_gt_u32_e64 s[62:63], v136, v0
	v_cmp_gt_u32_e64 s[64:65], v137, v0
	v_cmp_gt_u32_e64 s[66:67], v138, v0
	v_cmp_gt_u32_e64 s[68:69], v139, v0
	v_cmp_gt_u32_e64 s[70:71], v140, v0
	v_cmp_gt_u32_e64 s[72:73], v141, v0
	v_cmp_gt_u32_e64 s[74:75], v142, v0
	s_lshl_b32 s2, s9, 7
	v_add_u32_e32 v0, s86, v154
	v_add_u32_e32 v106, s2, v152
	v_subrev_u32_e32 v0, s2, v0
	s_lshl_b32 s2, s8, 8
	v_mov_b32_e32 v14, v1
	v_mov_b32_e32 v15, v1
	v_subrev_u32_e32 v163, s2, v0
	v_mov_b32_e32 v0, v1
	v_mov_b32_e32 v2, v1
	v_mov_b32_e32 v3, v1
	v_mov_b32_e32 v4, v1
	v_mov_b32_e32 v5, v1
	v_mov_b32_e32 v6, v1
	v_mov_b32_e32 v7, v1
	v_mov_b32_e32 v8, v1
	v_mov_b32_e32 v9, v1
	v_mov_b32_e32 v10, v1
	v_mov_b32_e32 v11, v1
	v_mov_b32_e32 v12, v1
	v_mov_b32_e32 v13, v1
	v_mov_b64_e32 v[32:33], v[14:15]
	s_lshr_b32 s84, s84, 6
	s_lshl_b32 s2, s8, 2
	v_mov_b64_e32 v[30:31], v[12:13]
	v_mov_b64_e32 v[28:29], v[10:11]
	v_mov_b64_e32 v[26:27], v[8:9]
	v_mov_b64_e32 v[24:25], v[6:7]
	v_mov_b64_e32 v[22:23], v[4:5]
	v_mov_b64_e32 v[20:21], v[2:3]
	v_mov_b64_e32 v[18:19], v[0:1]
	v_mov_b64_e32 v[16:17], v[14:15]
	s_sub_i32 s86, 0, s84
	s_sub_i32 s87, 0x7e, s2
	v_mov_b32_e32 v164, 0xff800000
	v_mov_b32_e32 v162, 0
	v_mov_b64_e32 v[14:15], v[12:13]
	v_mov_b64_e32 v[12:13], v[10:11]
	v_mov_b64_e32 v[10:11], v[8:9]
	v_mov_b64_e32 v[8:9], v[6:7]
	v_mov_b64_e32 v[6:7], v[4:5]
	v_mov_b64_e32 v[4:5], v[2:3]
	v_mov_b64_e32 v[2:3], v[0:1]

; #define LAS __attribute__((address_space(3)))
; __global__ void __launch_bounds__(512, 2) mega(Params p) {
;     extern __shared__ __attribute__((aligned(16))) unsigned char lds_raw[];
;     LAS unsigned char* lds = (LAS unsigned char*)lds_raw;
;     cg::grid_group grid = cg::this_grid();
;     const int G = gridDim.x, bx = blockIdx.x;
	.amdhsa_kernel _Z4mega6Params
		.amdhsa_group_segment_fixed_size 256
		.amdhsa_private_segment_fixed_size 0
		.amdhsa_kernarg_size 480
		.amdhsa_user_sgpr_count 2
		.amdhsa_user_sgpr_dispatch_ptr 0
		.amdhsa_user_sgpr_queue_ptr 0
		.amdhsa_user_sgpr_kernarg_segment_ptr 1
		.amdhsa_user_sgpr_dispatch_id 0
		.amdhsa_user_sgpr_kernarg_preload_length 0
		.amdhsa_user_sgpr_kernarg_preload_offset 0
		.amdhsa_user_sgpr_private_segment_size 0
		.amdhsa_uses_dynamic_stack 0
		.amdhsa_enable_private_segment 0
		.amdhsa_system_sgpr_workgroup_id_x 1
		.amdhsa_system_sgpr_workgroup_id_y 1
		.amdhsa_system_sgpr_workgroup_id_z 1
		.amdhsa_system_sgpr_workgroup_info 0
		.amdhsa_system_vgpr_workitem_id 2
		.amdhsa_next_free_vgpr 244
		.amdhsa_next_free_sgpr 102
		.amdhsa_accum_offset 244
		.amdhsa_reserve_vcc 1
		.amdhsa_float_round_mode_32 0
		.amdhsa_float_round_mode_16_64 0
		.amdhsa_float_denorm_mode_32 3
		.amdhsa_float_denorm_mode_16_64 3
		.amdhsa_dx10_clamp 1
		.amdhsa_ieee_mode 1
		.amdhsa_fp16_overflow 0
		.amdhsa_tg_split 0
		.amdhsa_exception_fp_ieee_invalid_op 0
		.amdhsa_exception_fp_denorm_src 0
		.amdhsa_exception_fp_ieee_div_zero 0
		.amdhsa_exception_fp_ieee_overflow 0
		.amdhsa_exception_fp_ieee_underflow 0
		.amdhsa_exception_fp_ieee_inexact 0
		.amdhsa_exception_int_div_zero 0
	.end_amdhsa_kernel

; #define LAS __attribute__((address_space(3)))
; __global__ void __launch_bounds__(512, 2) mega(Params p) {
;     extern __shared__ __attribute__((aligned(16))) unsigned char lds_raw[];
;     LAS unsigned char* lds = (LAS unsigned char*)lds_raw;
;     cg::grid_group grid = cg::this_grid();
;     const int G = gridDim.x, bx = blockIdx.x;
amdhsa.kernels:
  - .agpr_count:     0
    .args:
      - .offset:         0
        .size:           224
        .value_kind:     by_value
      - .offset:         224
        .size:           4
        .value_kind:     hidden_block_count_x
      - .offset:         228
        .size:           4
        .value_kind:     hidden_block_count_y
      - .offset:         232
        .size:           4
        .value_kind:     hidden_block_count_z
      - .offset:         236
        .size:           2
        .value_kind:     hidden_group_size_x
      - .offset:         238
        .size:           2
        .value_kind:     hidden_group_size_y
      - .offset:         240
        .size:           2
        .value_kind:     hidden_group_size_z
      - .offset:         242
        .size:           2
        .value_kind:     hidden_remainder_x
      - .offset:         244
        .size:           2
        .value_kind:     hidden_remainder_y
      - .offset:         246
        .size:           2
        .value_kind:     hidden_remainder_z
      - .offset:         264
        .size:           8
        .value_kind:     hidden_global_offset_x
      - .offset:         272
        .size:           8
        .value_kind:     hidden_global_offset_y
      - .offset:         280
        .size:           8
        .value_kind:     hidden_global_offset_z
      - .offset:         288
        .size:           2
        .value_kind:     hidden_grid_dims
      - .offset:         312
        .size:           8
        .value_kind:     hidden_multigrid_sync_arg
      - .offset:         344
        .size:           4
        .value_kind:     hidden_dynamic_lds_size
    .group_segment_fixed_size: 256
    .kernarg_segment_align: 8
    .kernarg_segment_size: 480
    .language:       OpenCL C
    .language_version:
      - 2
      - 0
    .max_flat_workgroup_size: 512
    .name:           _Z4mega6Params
    .private_segment_fixed_size: 0
    .sgpr_count:     108
    .sgpr_spill_count: 29
    .symbol:         _Z4mega6Params.kd
    .uniform_work_group_size: 1
    .uses_dynamic_stack: false
    .vgpr_count:     244
    .vgpr_spill_count: 0
    .wavefront_size: 64
